# dsa_attn: waves 4-7 start half a chunk later (s_sleep 56) so SIMD partners stop running the gather / LDS-stage / MFMA steps in lock-step
# baseline (speedup 1.0000x reference)
; #define LAS __attribute__((address_space(3)))
; __device__ __forceinline__ void dsa_attn_phase(const bf16_t* PJ, const float* rk, const unsigned short* SEL, const float* biasd, const float* qg, const float* kg, bf16_t* OL, LAS unsigned char* lds) {
;     ...
;     for (int e = tid; e < 2048; e += NTHR) biasS[e] = biasd[e];
;     if (tid < 16) biasS[2048 + tid] = -INFINITY;
;     __syncthreads();
;     LAS unsigned char* tile = lds + wid * 16896;
;     LAS int* selS = (LAS int*)(tile + 16384);
;     LAS float* rS = (LAS float*)(tile + 16384 + 256);
;     const int gw = blockIdx.x * NWAVE + wid, NGW = gridDim.x * NWAVE;
;     float bmax = -INFINITY;
; #pragma unroll 4
;     for (int d = G * 32; d < G * 32 + 32; ++d) bmax = fmaxf(bmax, biasS[d * 16 + c16]);
;     bmax = fmaxf(bmax, __shfl_xor(bmax, 16)); bmax = fmaxf(bmax, __shfl_xor(bmax, 32));
.LBB0_1095:
	s_or_b64 exec, exec, s[12:13]
	v_cmp_gt_i32_e32 vcc, 16, v0
	s_and_saveexec_b64 s[12:13], vcc
	s_add_i32 s0, 0, 0x21000
	v_lshl_add_u32 v1, v0, 2, s0
	v_mov_b32_e32 v2, 0xff800000
	ds_write_b32 v1, v2 offset:8192
	s_or_b64 exec, exec, s[12:13]
	v_bfe_u32 v1, v0, 4, 2
	v_lshlrev_b32_e32 v2, 5, v1
	v_and_b32_e32 v16, 15, v0
	s_add_i32 s0, 0, 0x21000
	v_or_b32_e32 v3, 1, v2
	v_mov_b32_e32 v8, 0xff800000
	v_and_b32_e32 v138, 63, v0
	v_lshl_add_u32 v139, v16, 2, s0
	v_mov_b32_e32 v9, v8
	s_mov_b32 s0, -8
	s_mov_b64 s[14:15], 0
	v_mov_b64_e32 v[12:13], v[2:3]
	s_waitcnt lgkmcnt(0)
	s_barrier
	v_readfirstlane_b32 s32, v194
	s_lshr_b32 s32, s32, 6
	s_cmp_lt_u32 s32, 4
	s_cbranch_scc1 .Lstag_dsa
	s_sleep 56
.Lstag_dsa:
	s_branch .LBB0_1101
